# HGRN combine item: the 34 decay vectors (identical for all waves) fetched once per block and broadcast through LDS instead of 8x through L1
# speedup vs baseline: 1.0295x; 1.0023x over previous
; DEV float bflo(unsigned w) { return __uint_as_float(w << 16); }
; DEV float bfhi(unsigned w) { return __uint_as_float(w & 0xffff0000u); }
; DEV void hg_combine_item(const Params& p, int item, int tid) {
;   const int e = (item * 512 + tid) * 2;
;   const int sc = e >> 12, el = e & 4095, d = el & 63;
;   u16* base = p.Sloc + (long)sc * NSEG * 4096 + el;
;   const float* db = p.Dseg + (long)sc * NSEG * 64 + d;
;   unsigned vals[NSEG - 1];
;   float2 dd[NSEG - 1];
; #pragma unroll
;   for (int k = 0; k < NSEG - 1; ++k) { vals[k] = *(const unsigned*)(base + (long)k * 4096); dd[k] = *(const float2*)(db + k * 64); }
;   float s0 = bflo(vals[0]), s1 = bfhi(vals[0]);
; #pragma unroll
;   for (int k = 1; k < NSEG - 1; ++k) {
;     s0 = fmaf(dd[k].x, s0, bflo(vals[k]));
;     s1 = fmaf(dd[k].y, s1, bfhi(vals[k]));
;     *(unsigned*)(base + (long)k * 4096) = pack2(s0, s1);
;   }
; }
.LBB0_979:
	s_add_i32 s7, s7, s6
	s_lshr_b32 s15, s8, 12
	s_and_b32 s16, s8, 0xfff
	s_add_i32 s8, s8, s9
	s_mul_i32 s18, s15, 0x48000
	s_lshl_b32 s16, s16, 1
	s_add_u32 s18, s18, s16
	s_add_u32 s10, s22, s18
	s_addc_u32 s11, s23, 0
	s_mul_i32 s18, s15, 0x2400
	s_add_u32 s12, s20, s18
	s_addc_u32 s13, s21, 0
	v_lshlrev_b32_e32 v0, 2, v197
	v_lshlrev_b32_e32 v1, 3, v197
	v_and_b32_e32 v1, 0xf8, v1
	s_barrier
	v_lshlrev_b32_e32 v111, 4, v197
	v_and_b32_e32 v112, 31, v197
	v_lshlrev_b32_e32 v112, 4, v112
	s_add_u32 s42, s12, 0x2100
	s_addc_u32 s43, s13, 0
	global_load_dwordx4 v[114:117], v111, s[12:13] offset:256
	global_load_dwordx4 v[118:121], v112, s[42:43]
	global_load_dword v2, v0, s[10:11]
	s_add_u32 s10, s10, 0x2000
	s_addc_u32 s11, s11, 0
	global_load_dword v3, v0, s[10:11]
	s_add_u32 s10, s10, 0x2000
	s_addc_u32 s11, s11, 0
	global_load_dword v4, v0, s[10:11]
	s_add_u32 s10, s10, 0x2000
	s_addc_u32 s11, s11, 0
	global_load_dword v5, v0, s[10:11]
	s_add_u32 s10, s10, 0x2000
	s_addc_u32 s11, s11, 0
	global_load_dword v6, v0, s[10:11]
	s_add_u32 s10, s10, 0x2000
	s_addc_u32 s11, s11, 0
	global_load_dword v7, v0, s[10:11]
	s_add_u32 s10, s10, 0x2000
	s_addc_u32 s11, s11, 0
	global_load_dword v8, v0, s[10:11]
	s_add_u32 s10, s10, 0x2000
	s_addc_u32 s11, s11, 0
	global_load_dword v9, v0, s[10:11]
	s_add_u32 s10, s10, 0x2000
	s_addc_u32 s11, s11, 0
	global_load_dword v10, v0, s[10:11]
	s_add_u32 s10, s10, 0x2000
	s_addc_u32 s11, s11, 0
	global_load_dword v11, v0, s[10:11]
	s_add_u32 s10, s10, 0x2000
	s_addc_u32 s11, s11, 0
	global_load_dword v12, v0, s[10:11]
	s_add_u32 s10, s10, 0x2000
	s_addc_u32 s11, s11, 0
	global_load_dword v13, v0, s[10:11]
	s_add_u32 s10, s10, 0x2000
	s_addc_u32 s11, s11, 0
	global_load_dword v14, v0, s[10:11]
	s_add_u32 s10, s10, 0x2000
	s_addc_u32 s11, s11, 0
	global_load_dword v15, v0, s[10:11]
	s_add_u32 s10, s10, 0x2000
	s_addc_u32 s11, s11, 0
	global_load_dword v16, v0, s[10:11]
	s_add_u32 s10, s10, 0x2000
	s_addc_u32 s11, s11, 0
	global_load_dword v17, v0, s[10:11]
	s_add_u32 s10, s10, 0x2000
	s_addc_u32 s11, s11, 0
	global_load_dword v18, v0, s[10:11]
	s_add_u32 s10, s10, 0x2000
	s_addc_u32 s11, s11, 0
	global_load_dword v19, v0, s[10:11]
	s_add_u32 s10, s10, 0x2000
	s_addc_u32 s11, s11, 0
	global_load_dword v20, v0, s[10:11]
	s_add_u32 s10, s10, 0x2000
	s_addc_u32 s11, s11, 0
	global_load_dword v21, v0, s[10:11]
	s_add_u32 s10, s10, 0x2000
	s_addc_u32 s11, s11, 0
	global_load_dword v22, v0, s[10:11]
	s_add_u32 s10, s10, 0x2000
	s_addc_u32 s11, s11, 0
	global_load_dword v23, v0, s[10:11]
	s_add_u32 s10, s10, 0x2000
	s_addc_u32 s11, s11, 0
	global_load_dword v24, v0, s[10:11]
	s_add_u32 s10, s10, 0x2000
	s_addc_u32 s11, s11, 0
	global_load_dword v25, v0, s[10:11]
	s_add_u32 s10, s10, 0x2000
	s_addc_u32 s11, s11, 0
	global_load_dword v26, v0, s[10:11]
	s_add_u32 s10, s10, 0x2000
	s_addc_u32 s11, s11, 0
	global_load_dword v27, v0, s[10:11]
	s_add_u32 s10, s10, 0x2000
	s_addc_u32 s11, s11, 0
	global_load_dword v28, v0, s[10:11]
	s_add_u32 s10, s10, 0x2000
	s_addc_u32 s11, s11, 0
	global_load_dword v29, v0, s[10:11]
	s_add_u32 s10, s10, 0x2000
	s_addc_u32 s11, s11, 0
	global_load_dword v30, v0, s[10:11]
	s_add_u32 s10, s10, 0x2000
	s_addc_u32 s11, s11, 0
	global_load_dword v31, v0, s[10:11]
	s_add_u32 s10, s10, 0x2000
	s_addc_u32 s11, s11, 0
	global_load_dword v32, v0, s[10:11]
	s_add_u32 s10, s10, 0x2000
	s_addc_u32 s11, s11, 0
	global_load_dword v33, v0, s[10:11]
	s_add_u32 s10, s10, 0x2000
	s_addc_u32 s11, s11, 0
	global_load_dword v34, v0, s[10:11]
	s_add_u32 s10, s10, 0x2000
	s_addc_u32 s11, s11, 0
	global_load_dword v35, v0, s[10:11]
	s_add_u32 s10, s10, 0x2000
	s_addc_u32 s11, s11, 0
	global_load_dword v36, v0, s[10:11]
	s_add_u32 s10, s10, 0x2000
	s_addc_u32 s11, s11, 0
	s_sub_u32 s18, s10, 0x44000
	s_subb_u32 s19, s11, 0
	s_waitcnt vmcnt(35)
	ds_write_b128 v111, v[114:117]
	v_add_u32_e32 v112, 0x2000, v112
	ds_write_b128 v112, v[118:121]
	s_waitcnt lgkmcnt(0)
	s_barrier
	ds_read_b64 v[38:39], v1 offset:0
	ds_read_b64 v[40:41], v1 offset:256
	ds_read_b64 v[42:43], v1 offset:512
	ds_read_b64 v[44:45], v1 offset:768
	ds_read_b64 v[46:47], v1 offset:1024
	ds_read_b64 v[48:49], v1 offset:1280
	ds_read_b64 v[50:51], v1 offset:1536
	ds_read_b64 v[52:53], v1 offset:1792
	ds_read_b64 v[54:55], v1 offset:2048
	ds_read_b64 v[56:57], v1 offset:2304
	ds_read_b64 v[58:59], v1 offset:2560
	ds_read_b64 v[60:61], v1 offset:2816
	s_waitcnt lgkmcnt(0)
	ds_read_b64 v[62:63], v1 offset:3072
	ds_read_b64 v[64:65], v1 offset:3328
	ds_read_b64 v[66:67], v1 offset:3584
	ds_read_b64 v[68:69], v1 offset:3840
	ds_read_b64 v[70:71], v1 offset:4096
	ds_read_b64 v[72:73], v1 offset:4352
	ds_read_b64 v[74:75], v1 offset:4608
	ds_read_b64 v[76:77], v1 offset:4864
	ds_read_b64 v[78:79], v1 offset:5120
	ds_read_b64 v[80:81], v1 offset:5376
	ds_read_b64 v[82:83], v1 offset:5632
	ds_read_b64 v[84:85], v1 offset:5888
	s_waitcnt lgkmcnt(0)
	ds_read_b64 v[86:87], v1 offset:6144
	ds_read_b64 v[88:89], v1 offset:6400
	ds_read_b64 v[90:91], v1 offset:6656
	ds_read_b64 v[92:93], v1 offset:6912
	ds_read_b64 v[94:95], v1 offset:7168
	ds_read_b64 v[96:97], v1 offset:7424
	ds_read_b64 v[98:99], v1 offset:7680
	ds_read_b64 v[100:101], v1 offset:7936
	ds_read_b64 v[102:103], v1 offset:8192
	ds_read_b64 v[104:105], v1 offset:8448
	s_waitcnt lgkmcnt(0)
	s_waitcnt vmcnt(34)
	v_lshlrev_b32_e32 v106, 16, v2
	v_and_b32_e32 v107, 0xffff0000, v2
	s_waitcnt vmcnt(33)
	v_lshlrev_b32_e32 v108, 16, v3
	v_and_b32_e32 v109, 0xffff0000, v3
	v_pk_fma_f32 v[106:107], v[38:39], v[106:107], v[108:109]
	v_cvt_pk_bf16_f32 v110, v106, v107
	global_store_dword v0, v110, s[18:19]
	s_add_u32 s18, s18, 0x2000
	s_addc_u32 s19, s19, 0
	s_waitcnt vmcnt(33)
; DEV float bflo(unsigned w) { return __uint_as_float(w << 16); }
; DEV float bfhi(unsigned w) { return __uint_as_float(w & 0xffff0000u); }
; DEV void hg_combine_item(const Params& p, int item, int tid) {
;     ...
;   float s0 = bflo(vals[0]), s1 = bfhi(vals[0]);
; #pragma unroll
;   for (int k = 1; k < NSEG - 1; ++k) {
;     s0 = fmaf(dd[k].x, s0, bflo(vals[k]));
;     s1 = fmaf(dd[k].y, s1, bfhi(vals[k]));
;     *(unsigned*)(base + (long)k * 4096) = pack2(s0, s1);
;   }
	v_lshlrev_b32_e32 v108, 16, v4
	v_and_b32_e32 v109, 0xffff0000, v4
	v_pk_fma_f32 v[106:107], v[40:41], v[106:107], v[108:109]
	v_cvt_pk_bf16_f32 v110, v106, v107
	global_store_dword v0, v110, s[18:19]
	s_add_u32 s18, s18, 0x2000
	s_addc_u32 s19, s19, 0
	s_waitcnt vmcnt(33)
	v_lshlrev_b32_e32 v108, 16, v5
	v_and_b32_e32 v109, 0xffff0000, v5
	v_pk_fma_f32 v[106:107], v[42:43], v[106:107], v[108:109]
	v_cvt_pk_bf16_f32 v110, v106, v107
	global_store_dword v0, v110, s[18:19]
	s_add_u32 s18, s18, 0x2000
	s_addc_u32 s19, s19, 0
	s_waitcnt vmcnt(33)
	v_lshlrev_b32_e32 v108, 16, v6
	v_and_b32_e32 v109, 0xffff0000, v6
	v_pk_fma_f32 v[106:107], v[44:45], v[106:107], v[108:109]
	v_cvt_pk_bf16_f32 v110, v106, v107
	global_store_dword v0, v110, s[18:19]
	s_add_u32 s18, s18, 0x2000
	s_addc_u32 s19, s19, 0
	s_waitcnt vmcnt(33)
	v_lshlrev_b32_e32 v108, 16, v7
	v_and_b32_e32 v109, 0xffff0000, v7
	v_pk_fma_f32 v[106:107], v[46:47], v[106:107], v[108:109]
	v_cvt_pk_bf16_f32 v110, v106, v107
	global_store_dword v0, v110, s[18:19]
	s_add_u32 s18, s18, 0x2000
	s_addc_u32 s19, s19, 0
	s_waitcnt vmcnt(33)
	v_lshlrev_b32_e32 v108, 16, v8
	v_and_b32_e32 v109, 0xffff0000, v8
	v_pk_fma_f32 v[106:107], v[48:49], v[106:107], v[108:109]
	v_cvt_pk_bf16_f32 v110, v106, v107
	global_store_dword v0, v110, s[18:19]
	s_add_u32 s18, s18, 0x2000
	s_addc_u32 s19, s19, 0
	s_waitcnt vmcnt(33)
	v_lshlrev_b32_e32 v108, 16, v9
	v_and_b32_e32 v109, 0xffff0000, v9
	v_pk_fma_f32 v[106:107], v[50:51], v[106:107], v[108:109]
	v_cvt_pk_bf16_f32 v110, v106, v107
	global_store_dword v0, v110, s[18:19]
	s_add_u32 s18, s18, 0x2000
	s_addc_u32 s19, s19, 0
	s_waitcnt vmcnt(33)
	v_lshlrev_b32_e32 v108, 16, v10
	v_and_b32_e32 v109, 0xffff0000, v10
	v_pk_fma_f32 v[106:107], v[52:53], v[106:107], v[108:109]
	v_cvt_pk_bf16_f32 v110, v106, v107
	global_store_dword v0, v110, s[18:19]
	s_add_u32 s18, s18, 0x2000
	s_addc_u32 s19, s19, 0
	s_waitcnt vmcnt(33)
	v_lshlrev_b32_e32 v108, 16, v11
	v_and_b32_e32 v109, 0xffff0000, v11
	v_pk_fma_f32 v[106:107], v[54:55], v[106:107], v[108:109]
	v_cvt_pk_bf16_f32 v110, v106, v107
	global_store_dword v0, v110, s[18:19]
	s_add_u32 s18, s18, 0x2000
	s_addc_u32 s19, s19, 0
	s_waitcnt vmcnt(33)
	v_lshlrev_b32_e32 v108, 16, v12
	v_and_b32_e32 v109, 0xffff0000, v12
	v_pk_fma_f32 v[106:107], v[56:57], v[106:107], v[108:109]
	v_cvt_pk_bf16_f32 v110, v106, v107
	global_store_dword v0, v110, s[18:19]
	s_add_u32 s18, s18, 0x2000
	s_addc_u32 s19, s19, 0
	s_waitcnt vmcnt(33)
	v_lshlrev_b32_e32 v108, 16, v13
	v_and_b32_e32 v109, 0xffff0000, v13
	v_pk_fma_f32 v[106:107], v[58:59], v[106:107], v[108:109]
	v_cvt_pk_bf16_f32 v110, v106, v107
	global_store_dword v0, v110, s[18:19]
	s_add_u32 s18, s18, 0x2000
	s_addc_u32 s19, s19, 0
	s_waitcnt vmcnt(33)
	v_lshlrev_b32_e32 v108, 16, v14
	v_and_b32_e32 v109, 0xffff0000, v14
	v_pk_fma_f32 v[106:107], v[60:61], v[106:107], v[108:109]
	v_cvt_pk_bf16_f32 v110, v106, v107
	global_store_dword v0, v110, s[18:19]
	s_add_u32 s18, s18, 0x2000
	s_addc_u32 s19, s19, 0
	s_waitcnt vmcnt(33)
	v_lshlrev_b32_e32 v108, 16, v15
	v_and_b32_e32 v109, 0xffff0000, v15
	v_pk_fma_f32 v[106:107], v[62:63], v[106:107], v[108:109]
	v_cvt_pk_bf16_f32 v110, v106, v107
	global_store_dword v0, v110, s[18:19]
	s_add_u32 s18, s18, 0x2000
	s_addc_u32 s19, s19, 0
	s_waitcnt vmcnt(33)
	v_lshlrev_b32_e32 v108, 16, v16
	v_and_b32_e32 v109, 0xffff0000, v16
	v_pk_fma_f32 v[106:107], v[64:65], v[106:107], v[108:109]
	v_cvt_pk_bf16_f32 v110, v106, v107
	global_store_dword v0, v110, s[18:19]
	s_add_u32 s18, s18, 0x2000
	s_addc_u32 s19, s19, 0
	s_waitcnt vmcnt(33)
	v_lshlrev_b32_e32 v108, 16, v17
	v_and_b32_e32 v109, 0xffff0000, v17
	v_pk_fma_f32 v[106:107], v[66:67], v[106:107], v[108:109]
	v_cvt_pk_bf16_f32 v110, v106, v107
	global_store_dword v0, v110, s[18:19]
	s_add_u32 s18, s18, 0x2000
	s_addc_u32 s19, s19, 0
	s_waitcnt vmcnt(33)
	v_lshlrev_b32_e32 v108, 16, v18
	v_and_b32_e32 v109, 0xffff0000, v18
	v_pk_fma_f32 v[106:107], v[68:69], v[106:107], v[108:109]
	v_cvt_pk_bf16_f32 v110, v106, v107
	global_store_dword v0, v110, s[18:19]
	s_add_u32 s18, s18, 0x2000
	s_addc_u32 s19, s19, 0
	s_waitcnt vmcnt(33)
	v_lshlrev_b32_e32 v108, 16, v19
	v_and_b32_e32 v109, 0xffff0000, v19
	v_pk_fma_f32 v[106:107], v[70:71], v[106:107], v[108:109]
	v_cvt_pk_bf16_f32 v110, v106, v107
	global_store_dword v0, v110, s[18:19]
	s_add_u32 s18, s18, 0x2000
	s_addc_u32 s19, s19, 0
	s_waitcnt vmcnt(33)
	v_lshlrev_b32_e32 v108, 16, v20
	v_and_b32_e32 v109, 0xffff0000, v20
	v_pk_fma_f32 v[106:107], v[72:73], v[106:107], v[108:109]
	v_cvt_pk_bf16_f32 v110, v106, v107
	global_store_dword v0, v110, s[18:19]
	s_add_u32 s18, s18, 0x2000
	s_addc_u32 s19, s19, 0
	s_waitcnt vmcnt(33)
; DEV float bflo(unsigned w) { return __uint_as_float(w << 16); }
; DEV float bfhi(unsigned w) { return __uint_as_float(w & 0xffff0000u); }
; DEV void hg_combine_item(const Params& p, int item, int tid) {
;     ...
;   float s0 = bflo(vals[0]), s1 = bfhi(vals[0]);
; #pragma unroll
;   for (int k = 1; k < NSEG - 1; ++k) {
;     s0 = fmaf(dd[k].x, s0, bflo(vals[k]));
;     s1 = fmaf(dd[k].y, s1, bfhi(vals[k]));
;     *(unsigned*)(base + (long)k * 4096) = pack2(s0, s1);
;   }
	v_lshlrev_b32_e32 v108, 16, v21
	v_and_b32_e32 v109, 0xffff0000, v21
	v_pk_fma_f32 v[106:107], v[74:75], v[106:107], v[108:109]
	v_cvt_pk_bf16_f32 v110, v106, v107
	global_store_dword v0, v110, s[18:19]
	s_add_u32 s18, s18, 0x2000
	s_addc_u32 s19, s19, 0
	s_waitcnt vmcnt(33)
	v_lshlrev_b32_e32 v108, 16, v22
	v_and_b32_e32 v109, 0xffff0000, v22
	v_pk_fma_f32 v[106:107], v[76:77], v[106:107], v[108:109]
	v_cvt_pk_bf16_f32 v110, v106, v107
	global_store_dword v0, v110, s[18:19]
	s_add_u32 s18, s18, 0x2000
	s_addc_u32 s19, s19, 0
	s_waitcnt vmcnt(33)
	v_lshlrev_b32_e32 v108, 16, v23
	v_and_b32_e32 v109, 0xffff0000, v23
	v_pk_fma_f32 v[106:107], v[78:79], v[106:107], v[108:109]
	v_cvt_pk_bf16_f32 v110, v106, v107
	global_store_dword v0, v110, s[18:19]
	s_add_u32 s18, s18, 0x2000
	s_addc_u32 s19, s19, 0
	s_waitcnt vmcnt(33)
	v_lshlrev_b32_e32 v108, 16, v24
	v_and_b32_e32 v109, 0xffff0000, v24
	v_pk_fma_f32 v[106:107], v[80:81], v[106:107], v[108:109]
	v_cvt_pk_bf16_f32 v110, v106, v107
	global_store_dword v0, v110, s[18:19]
	s_add_u32 s18, s18, 0x2000
	s_addc_u32 s19, s19, 0
	s_waitcnt vmcnt(33)
	v_lshlrev_b32_e32 v108, 16, v25
	v_and_b32_e32 v109, 0xffff0000, v25
	v_pk_fma_f32 v[106:107], v[82:83], v[106:107], v[108:109]
	v_cvt_pk_bf16_f32 v110, v106, v107
	global_store_dword v0, v110, s[18:19]
	s_add_u32 s18, s18, 0x2000
	s_addc_u32 s19, s19, 0
	s_waitcnt vmcnt(33)
	v_lshlrev_b32_e32 v108, 16, v26
	v_and_b32_e32 v109, 0xffff0000, v26
	v_pk_fma_f32 v[106:107], v[84:85], v[106:107], v[108:109]
	v_cvt_pk_bf16_f32 v110, v106, v107
	global_store_dword v0, v110, s[18:19]
	s_add_u32 s18, s18, 0x2000
	s_addc_u32 s19, s19, 0
	s_waitcnt vmcnt(33)
	v_lshlrev_b32_e32 v108, 16, v27
	v_and_b32_e32 v109, 0xffff0000, v27
	v_pk_fma_f32 v[106:107], v[86:87], v[106:107], v[108:109]
	v_cvt_pk_bf16_f32 v110, v106, v107
	global_store_dword v0, v110, s[18:19]
	s_add_u32 s18, s18, 0x2000
	s_addc_u32 s19, s19, 0
	s_waitcnt vmcnt(33)
	v_lshlrev_b32_e32 v108, 16, v28
	v_and_b32_e32 v109, 0xffff0000, v28
	v_pk_fma_f32 v[106:107], v[88:89], v[106:107], v[108:109]
	v_cvt_pk_bf16_f32 v110, v106, v107
	global_store_dword v0, v110, s[18:19]
	s_add_u32 s18, s18, 0x2000
	s_addc_u32 s19, s19, 0
	s_waitcnt vmcnt(33)
	v_lshlrev_b32_e32 v108, 16, v29
	v_and_b32_e32 v109, 0xffff0000, v29
	v_pk_fma_f32 v[106:107], v[90:91], v[106:107], v[108:109]
	v_cvt_pk_bf16_f32 v110, v106, v107
	global_store_dword v0, v110, s[18:19]
	s_add_u32 s18, s18, 0x2000
	s_addc_u32 s19, s19, 0
	s_waitcnt vmcnt(33)
	v_lshlrev_b32_e32 v108, 16, v30
	v_and_b32_e32 v109, 0xffff0000, v30
	v_pk_fma_f32 v[106:107], v[92:93], v[106:107], v[108:109]
	v_cvt_pk_bf16_f32 v110, v106, v107
	global_store_dword v0, v110, s[18:19]
	s_add_u32 s18, s18, 0x2000
	s_addc_u32 s19, s19, 0
	s_waitcnt vmcnt(33)
	v_lshlrev_b32_e32 v108, 16, v31
	v_and_b32_e32 v109, 0xffff0000, v31
	v_pk_fma_f32 v[106:107], v[94:95], v[106:107], v[108:109]
	v_cvt_pk_bf16_f32 v110, v106, v107
	global_store_dword v0, v110, s[18:19]
	s_add_u32 s18, s18, 0x2000
	s_addc_u32 s19, s19, 0
	s_waitcnt vmcnt(33)
	v_lshlrev_b32_e32 v108, 16, v32
	v_and_b32_e32 v109, 0xffff0000, v32
	v_pk_fma_f32 v[106:107], v[96:97], v[106:107], v[108:109]
	v_cvt_pk_bf16_f32 v110, v106, v107
	global_store_dword v0, v110, s[18:19]
	s_add_u32 s18, s18, 0x2000
	s_addc_u32 s19, s19, 0
	s_waitcnt vmcnt(33)
	v_lshlrev_b32_e32 v108, 16, v33
	v_and_b32_e32 v109, 0xffff0000, v33
	v_pk_fma_f32 v[106:107], v[98:99], v[106:107], v[108:109]
	v_cvt_pk_bf16_f32 v110, v106, v107
	global_store_dword v0, v110, s[18:19]
	s_add_u32 s18, s18, 0x2000
	s_addc_u32 s19, s19, 0
	s_waitcnt vmcnt(33)
	v_lshlrev_b32_e32 v108, 16, v34
	v_and_b32_e32 v109, 0xffff0000, v34
	v_pk_fma_f32 v[106:107], v[100:101], v[106:107], v[108:109]
	v_cvt_pk_bf16_f32 v110, v106, v107
	global_store_dword v0, v110, s[18:19]
	s_add_u32 s18, s18, 0x2000
	s_addc_u32 s19, s19, 0
	s_waitcnt vmcnt(33)
	v_lshlrev_b32_e32 v108, 16, v35
	v_and_b32_e32 v109, 0xffff0000, v35
	v_pk_fma_f32 v[106:107], v[102:103], v[106:107], v[108:109]
	v_cvt_pk_bf16_f32 v110, v106, v107
	global_store_dword v0, v110, s[18:19]
	s_add_u32 s18, s18, 0x2000
	s_addc_u32 s19, s19, 0
	s_waitcnt vmcnt(33)
	v_lshlrev_b32_e32 v108, 16, v36
	v_and_b32_e32 v109, 0xffff0000, v36
	v_pk_fma_f32 v[106:107], v[104:105], v[106:107], v[108:109]
	v_cvt_pk_bf16_f32 v110, v106, v107
	global_store_dword v0, v110, s[18:19]
	s_add_u32 s18, s18, 0x2000
	s_addc_u32 s19, s19, 0
	s_cmp_lt_i32 s7, 64
	s_cbranch_scc1 .LBB0_979
